# stack + final LayerNorm loop: next row's loads issued right after the current row is unpacked (software prefetch)
# baseline (speedup 1.0000x reference)
.LBB0_1216:
	s_or_b64 exec, exec, s[0:1]
	s_and_b64 vcc, exec, s[86:87]
	s_waitcnt lgkmcnt(0)
	s_barrier
	s_cbranch_vccnz .LBB0_1219
	v_lshlrev_b32_e32 v32, 3, v168
	v_ashrrev_i32_e32 v33, 31, v32
	v_lshlrev_b64 v[34:35], 2, v[32:33]
	v_lshl_add_u64 v[0:1], s[14:15], 0, v[34:35]
	s_mov_b64 s[0:1], 0x1000
	v_add_co_u32_e32 v18, vcc, 0x1000, v0
	v_lshl_add_u64 v[16:17], v[0:1], 0, s[0:1]
	s_nop 0
	v_addc_co_u32_e32 v19, vcc, 0, v1, vcc
	s_movk_i32 s2, 0x1000
	global_load_dwordx4 v[0:3], v[18:19], off
	global_load_dwordx4 v[4:7], v[16:17], off offset:2064
	global_load_dwordx4 v[8:11], v[16:17], off offset:16
	global_load_dwordx4 v[12:15], v[16:17], off offset:2048
	v_lshl_add_u64 v[16:17], s[16:17], 0, v[34:35]
	v_lshl_add_u64 v[36:37], v[16:17], 0, s[0:1]
	v_add_co_u32_e32 v38, vcc, s2, v16
	s_ashr_i32 s81, s80, 31
	s_nop 0
	v_addc_co_u32_e32 v39, vcc, 0, v17, vcc
	global_load_dwordx4 v[16:19], v[36:37], off offset:2064
	global_load_dwordx4 v[20:23], v[38:39], off
	global_load_dwordx4 v[24:27], v[36:37], off offset:2048
	global_load_dwordx4 v[28:31], v[36:37], off offset:16
	v_mbcnt_lo_u32_b32 v36, -1, 0
	v_mbcnt_hi_u32_b32 v41, -1, v36
	v_and_b32_e32 v36, 64, v41
	v_add_u32_e32 v42, 64, v36
	v_xor_b32_e32 v36, 1, v41
	v_cmp_lt_i32_e32 vcc, v36, v42
	v_xor_b32_e32 v37, 2, v41
	s_lshl_b64 s[0:1], s[80:81], 11
	v_cndmask_b32_e32 v36, v41, v36, vcc
	v_cmp_lt_i32_e32 vcc, v37, v42
	v_xor_b32_e32 v38, 4, v41
	s_add_u32 s0, s20, s0
	v_cndmask_b32_e32 v37, v41, v37, vcc
	v_cmp_lt_i32_e32 vcc, v38, v42
	v_xor_b32_e32 v39, 8, v41
	s_addc_u32 s1, s21, s1
	v_cndmask_b32_e32 v38, v41, v38, vcc
	v_cmp_lt_i32_e32 vcc, v39, v42
	v_xor_b32_e32 v40, 16, v41
	v_lshl_add_u64 v[32:33], v[32:33], 1, s[0:1]
	s_mov_b64 s[0:1], 0x17100000
	s_ashr_i32 s79, s78, 31
	v_cndmask_b32_e32 v39, v41, v39, vcc
	v_cmp_lt_i32_e32 vcc, v40, v42
	v_xor_b32_e32 v43, 32, v41
	v_lshl_add_u64 v[32:33], v[32:33], 0, s[0:1]
	s_lshl_b64 s[2:3], s[78:79], 11
	s_lshl_b64 s[0:1], s[80:81], 12
	v_cndmask_b32_e32 v40, v41, v40, vcc
	v_cmp_lt_i32_e32 vcc, v43, v42
	s_add_u32 s0, s18, s0
	s_addc_u32 s1, s19, s1
	v_cndmask_b32_e32 v41, v41, v43, vcc
	v_lshlrev_b32_e32 v36, 2, v36
	v_lshlrev_b32_e32 v37, 2, v37
	v_lshlrev_b32_e32 v38, 2, v38
	v_lshlrev_b32_e32 v39, 2, v39
	v_lshlrev_b32_e32 v40, 2, v40
	v_lshlrev_b32_e32 v41, 2, v41
	v_lshl_add_u64 v[34:35], s[0:1], 0, v[34:35]
	s_lshl_b64 s[4:5], s[78:79], 12
	v_mov_b32_e32 v42, 0x3727c5ac
	s_mov_b32 s6, 0xf800000
	v_mov_b32_e32 v43, 0x260
	global_load_dwordx4 v[76:79], v[32:33], off
	global_load_dwordx4 v[80:83], v[32:33], off offset:1024
	v_lshl_add_u64 v[32:33], v[32:33], 0, s[2:3]
	s_waitcnt vmcnt(0)
.LBB0_1218:
	s_add_i32 s80, s80, s78
	s_cmp_lt_i32 s80, 0x8000
	s_waitcnt vmcnt(5)
	v_lshlrev_b32_e32 v58, 16, v76
	v_and_b32_e32 v59, 0xffff0000, v76
	v_add_f32_e32 v60, 0, v58
	v_lshlrev_b32_e32 v44, 16, v77
	v_add_f32_e32 v60, v60, v59
	v_and_b32_e32 v45, 0xffff0000, v77
	v_add_f32_e32 v60, v60, v44
	v_lshlrev_b32_e32 v56, 16, v78
	v_add_f32_e32 v60, v60, v45
	v_and_b32_e32 v57, 0xffff0000, v78
	v_add_f32_e32 v60, v60, v56
	v_lshlrev_b32_e32 v46, 16, v79
	v_add_f32_e32 v60, v60, v57
	v_and_b32_e32 v47, 0xffff0000, v79
	v_add_f32_e32 v60, v60, v46
	s_waitcnt vmcnt(4)
	v_lshlrev_b32_e32 v54, 16, v80
	v_add_f32_e32 v60, v60, v47
	v_and_b32_e32 v55, 0xffff0000, v80
	v_add_f32_e32 v60, v60, v54
	v_lshlrev_b32_e32 v48, 16, v81
	v_add_f32_e32 v60, v60, v55
	v_and_b32_e32 v49, 0xffff0000, v81
	v_add_f32_e32 v60, v60, v48
	v_lshlrev_b32_e32 v52, 16, v82
	v_add_f32_e32 v60, v60, v49
	v_and_b32_e32 v53, 0xffff0000, v82
	v_add_f32_e32 v60, v60, v52
	v_lshlrev_b32_e32 v50, 16, v83
	v_add_f32_e32 v60, v60, v53
	v_and_b32_e32 v51, 0xffff0000, v83
	global_load_dwordx4 v[76:79], v[32:33], off
	global_load_dwordx4 v[80:83], v[32:33], off offset:1024
	v_lshl_add_u64 v[32:33], v[32:33], 0, s[2:3]
	v_add_f32_e32 v60, v60, v50
	v_add_f32_e32 v60, v60, v51
	ds_bpermute_b32 v61, v36, v60
	s_waitcnt lgkmcnt(0)
	v_add_f32_e32 v60, v60, v61
	ds_bpermute_b32 v61, v37, v60
	s_waitcnt lgkmcnt(0)
	v_add_f32_e32 v60, v60, v61
	ds_bpermute_b32 v61, v38, v60
	s_waitcnt lgkmcnt(0)
	v_add_f32_e32 v60, v60, v61
	ds_bpermute_b32 v61, v39, v60
	s_waitcnt lgkmcnt(0)
	v_add_f32_e32 v60, v60, v61
	ds_bpermute_b32 v61, v40, v60
	s_waitcnt lgkmcnt(0)
	v_add_f32_e32 v60, v60, v61
	ds_bpermute_b32 v61, v41, v60
	s_waitcnt lgkmcnt(0)
	v_add_f32_e32 v60, v60, v61
	v_mul_f32_e32 v60, 0x3a800000, v60
	v_pk_add_f32 v[58:59], v[58:59], v[60:61] op_sel_hi:[1,0] neg_lo:[0,1] neg_hi:[0,1]
	v_pk_add_f32 v[44:45], v[44:45], v[60:61] op_sel_hi:[1,0] neg_lo:[0,1] neg_hi:[0,1]
	v_pk_add_f32 v[56:57], v[56:57], v[60:61] op_sel_hi:[1,0] neg_lo:[0,1] neg_hi:[0,1]
	v_pk_add_f32 v[46:47], v[46:47], v[60:61] op_sel_hi:[1,0] neg_lo:[0,1] neg_hi:[0,1]
	v_pk_add_f32 v[54:55], v[54:55], v[60:61] op_sel_hi:[1,0] neg_lo:[0,1] neg_hi:[0,1]
	v_pk_add_f32 v[48:49], v[48:49], v[60:61] op_sel_hi:[1,0] neg_lo:[0,1] neg_hi:[0,1]
	v_pk_add_f32 v[52:53], v[52:53], v[60:61] op_sel_hi:[1,0] neg_lo:[0,1] neg_hi:[0,1]
	v_pk_add_f32 v[50:51], v[50:51], v[60:61] op_sel_hi:[1,0] neg_lo:[0,1] neg_hi:[0,1]
	v_pk_mul_f32 v[60:61], v[58:59], v[58:59]
	v_pk_mul_f32 v[62:63], v[44:45], v[44:45]
	v_add_f32_e32 v60, v60, v61
	v_add_f32_e32 v60, v62, v60
	v_pk_mul_f32 v[64:65], v[56:57], v[56:57]
	v_add_f32_e32 v60, v63, v60
	v_add_f32_e32 v60, v64, v60
	v_pk_mul_f32 v[66:67], v[46:47], v[46:47]
	v_add_f32_e32 v60, v65, v60
	v_add_f32_e32 v60, v66, v60
	v_pk_mul_f32 v[68:69], v[54:55], v[54:55]
	v_add_f32_e32 v60, v67, v60
	v_add_f32_e32 v60, v68, v60
	v_pk_mul_f32 v[70:71], v[48:49], v[48:49]
	v_add_f32_e32 v60, v69, v60
	v_add_f32_e32 v60, v70, v60
	v_pk_mul_f32 v[72:73], v[52:53], v[52:53]
	v_add_f32_e32 v60, v71, v60
	v_add_f32_e32 v60, v72, v60
	v_pk_mul_f32 v[74:75], v[50:51], v[50:51]
	v_add_f32_e32 v60, v73, v60
	v_add_f32_e32 v60, v74, v60
	v_add_f32_e32 v60, v75, v60
	ds_bpermute_b32 v61, v36, v60
	s_waitcnt lgkmcnt(0)
	v_add_f32_e32 v60, v60, v61
	ds_bpermute_b32 v61, v37, v60
	s_waitcnt lgkmcnt(0)
	v_add_f32_e32 v60, v60, v61
	ds_bpermute_b32 v61, v38, v60
	s_waitcnt lgkmcnt(0)
	v_add_f32_e32 v60, v60, v61
	ds_bpermute_b32 v61, v39, v60
	s_waitcnt lgkmcnt(0)
	v_add_f32_e32 v60, v60, v61
	ds_bpermute_b32 v61, v40, v60
	s_waitcnt lgkmcnt(0)
	v_add_f32_e32 v60, v60, v61
	ds_bpermute_b32 v61, v41, v60
	s_waitcnt lgkmcnt(0)
	v_add_f32_e32 v60, v60, v61
	v_fmamk_f32 v60, v60, 0x3a800000, v42
	v_mul_f32_e32 v61, 0x4f800000, v60
	v_cmp_gt_f32_e32 vcc, s6, v60
	s_nop 1
	v_cndmask_b32_e32 v60, v60, v61, vcc
	v_sqrt_f32_e32 v61, v60
	s_nop 0
	v_add_u32_e32 v62, -1, v61
	v_add_u32_e32 v63, 1, v61
	v_fma_f32 v64, -v62, v61, v60
	v_fma_f32 v65, -v63, v61, v60
	v_cmp_ge_f32_e64 s[0:1], 0, v64
	s_nop 1
	v_cndmask_b32_e64 v61, v61, v62, s[0:1]
	v_cmp_lt_f32_e64 s[0:1], 0, v65
	s_nop 1
	v_cndmask_b32_e64 v61, v61, v63, s[0:1]
	v_mul_f32_e32 v62, 0x37800000, v61
	v_cndmask_b32_e32 v61, v61, v62, vcc
	v_cmp_class_f32_e32 vcc, v60, v43
	s_nop 1
	v_cndmask_b32_e32 v60, v61, v60, vcc
	v_div_scale_f32 v61, s[0:1], v60, v60, 1.0
	v_rcp_f32_e32 v63, v61
	v_div_scale_f32 v62, vcc, 1.0, v60, 1.0
	v_fma_f32 v64, -v61, v63, 1.0
	v_fmac_f32_e32 v63, v64, v63
	v_mul_f32_e32 v64, v62, v63
	v_fma_f32 v65, -v61, v64, v62
	v_fmac_f32_e32 v64, v65, v63
	v_fma_f32 v61, -v61, v64, v62
	v_div_fmas_f32 v61, v61, v63, v64
	v_div_fixup_f32 v60, v61, v60, 1.0
	v_pk_mul_f32 v[58:59], v[58:59], v[60:61] op_sel_hi:[1,0]
	v_pk_mul_f32 v[44:45], v[44:45], v[60:61] op_sel_hi:[1,0]
	v_pk_mul_f32 v[56:57], v[56:57], v[60:61] op_sel_hi:[1,0]
	v_pk_mul_f32 v[62:63], v[46:47], v[60:61] op_sel_hi:[1,0]
	v_pk_mul_f32 v[64:65], v[54:55], v[60:61] op_sel_hi:[1,0]
	v_pk_mul_f32 v[54:55], v[48:49], v[60:61] op_sel_hi:[1,0]
	v_pk_mul_f32 v[66:67], v[52:53], v[60:61] op_sel_hi:[1,0]
	v_pk_mul_f32 v[60:61], v[50:51], v[60:61] op_sel_hi:[1,0]
	v_pk_fma_f32 v[46:47], v[2:3], v[44:45], v[22:23]
	v_pk_fma_f32 v[44:45], v[0:1], v[58:59], v[20:21]
	v_pk_fma_f32 v[50:51], v[10:11], v[62:63], v[30:31]
	v_pk_fma_f32 v[48:49], v[8:9], v[56:57], v[28:29]
	v_pk_fma_f32 v[54:55], v[14:15], v[54:55], v[26:27]
	v_pk_fma_f32 v[52:53], v[12:13], v[64:65], v[24:25]
	v_pk_fma_f32 v[58:59], v[6:7], v[60:61], v[18:19]
	v_pk_fma_f32 v[56:57], v[4:5], v[66:67], v[16:17]
	global_store_dwordx4 v[34:35], v[44:47], off nt
	global_store_dwordx4 v[34:35], v[48:51], off offset:16 nt
	global_store_dwordx4 v[34:35], v[52:55], off offset:2048 nt
	global_store_dwordx4 v[34:35], v[56:59], off offset:2064 nt
	v_lshl_add_u64 v[34:35], v[34:35], 0, s[4:5]
	s_cbranch_scc1 .LBB0_1218
.LBB0_1219:
	s_waitcnt vmcnt(0)
	s_endpgm
